# sample-MLA score block: K fragments double-buffered (two LDS reads in flight per dependent MFMA) + G2 loop + lean past-K epilogue
# speedup vs baseline: 1.0122x; 1.0026x over previous
.LBB0_1144:
	s_mul_hi_u32 s19, s17, 0xcccccccd
	s_lshr_b32 s19, s19, 2
	s_mul_i32 s19, s19, 0x14000
	v_subrev_u32_e32 v142, s19, v240
	s_mul_hi_u32 s19, s25, 0xcccccccd
	s_lshr_b32 s19, s19, 2
	s_mul_i32 s19, s19, 0x14000
	v_subrev_u32_e32 v143, s19, v241
	s_add_i32 s19, s9, 0
	s_waitcnt lgkmcnt(0)
	v_add_u32_e32 v200, s19, v143
	v_add_u32_e32 v1, s19, v142
	ds_read_b64_tr_b16 v[142:143], v200 offset:0
	ds_read_b64_tr_b16 v[144:145], v200 offset:8192
	ds_read_b64_tr_b16 v[146:147], v200 offset:512
	ds_read_b64_tr_b16 v[148:149], v200 offset:8704
	ds_read_b64_tr_b16 v[248:249], v200 offset:1024
	ds_read_b64_tr_b16 v[250:251], v200 offset:9216
	s_setprio 1
	ds_read_b64_tr_b16 v[204:205], v200 offset:1536
	ds_read_b64_tr_b16 v[206:207], v200 offset:9728
	s_waitcnt lgkmcnt(6)
	v_mfma_f32_32x32x16_bf16 v[6:21], v[138:141], v[142:145], v[6:21]
	ds_read_b64_tr_b16 v[142:143], v200 offset:2048
	ds_read_b64_tr_b16 v[144:145], v200 offset:10240
	s_waitcnt lgkmcnt(6)
	v_mfma_f32_32x32x16_bf16 v[118:133], v[138:141], v[146:149], v[118:133]
	ds_read_b64_tr_b16 v[146:147], v200 offset:2560
	ds_read_b64_tr_b16 v[148:149], v200 offset:10752
	s_waitcnt lgkmcnt(6)
	v_mfma_f32_32x32x16_bf16 v[102:117], v[138:141], v[248:251], v[102:117]
	ds_read_b64_tr_b16 v[248:249], v200 offset:3072
	ds_read_b64_tr_b16 v[250:251], v200 offset:11264
	s_waitcnt lgkmcnt(6)
	v_mfma_f32_32x32x16_bf16 v[86:101], v[138:141], v[204:207], v[86:101]
	ds_read_b64_tr_b16 v[204:205], v200 offset:3584
	ds_read_b64_tr_b16 v[206:207], v200 offset:11776
	s_waitcnt lgkmcnt(6)
	v_mfma_f32_32x32x16_bf16 v[70:85], v[138:141], v[142:145], v[70:85]
	ds_read_b64_tr_b16 v[142:143], v1 offset:0
	ds_read_b64_tr_b16 v[144:145], v1 offset:8192
	s_waitcnt lgkmcnt(6)
	v_mfma_f32_32x32x16_bf16 v[54:69], v[138:141], v[146:149], v[54:69]
	ds_read_b64_tr_b16 v[146:147], v1 offset:512
	ds_read_b64_tr_b16 v[148:149], v1 offset:8704
	s_waitcnt lgkmcnt(6)
	v_mfma_f32_32x32x16_bf16 v[38:53], v[138:141], v[248:251], v[38:53]
	ds_read_b64_tr_b16 v[248:249], v1 offset:1024
	ds_read_b64_tr_b16 v[250:251], v1 offset:9216
	s_waitcnt lgkmcnt(6)
	v_mfma_f32_32x32x16_bf16 v[22:37], v[138:141], v[204:207], v[22:37]
	ds_read_b64_tr_b16 v[204:205], v1 offset:1536
	ds_read_b64_tr_b16 v[206:207], v1 offset:9728
	s_waitcnt lgkmcnt(6)
	v_mfma_f32_32x32x16_bf16 v[6:21], v[134:137], v[142:145], v[6:21]
	ds_read_b64_tr_b16 v[142:143], v1 offset:2048
	ds_read_b64_tr_b16 v[144:145], v1 offset:10240
	s_waitcnt lgkmcnt(6)
	v_mfma_f32_32x32x16_bf16 v[118:133], v[134:137], v[146:149], v[118:133]
	ds_read_b64_tr_b16 v[146:147], v1 offset:2560
	ds_read_b64_tr_b16 v[148:149], v1 offset:10752
	s_waitcnt lgkmcnt(6)
	v_mfma_f32_32x32x16_bf16 v[102:117], v[134:137], v[248:251], v[102:117]
	ds_read_b64_tr_b16 v[248:249], v1 offset:3072
	ds_read_b64_tr_b16 v[250:251], v1 offset:11264
	s_waitcnt lgkmcnt(6)
	v_mfma_f32_32x32x16_bf16 v[86:101], v[134:137], v[204:207], v[86:101]
	ds_read_b64_tr_b16 v[204:205], v1 offset:3584
	ds_read_b64_tr_b16 v[206:207], v1 offset:11776
	s_waitcnt lgkmcnt(6)
	v_mfma_f32_32x32x16_bf16 v[70:85], v[134:137], v[142:145], v[70:85]
	s_waitcnt lgkmcnt(4)
	v_mfma_f32_32x32x16_bf16 v[54:69], v[134:137], v[146:149], v[54:69]
	s_waitcnt lgkmcnt(2)
	v_mfma_f32_32x32x16_bf16 v[38:53], v[134:137], v[248:251], v[38:53]
	s_waitcnt lgkmcnt(0)
	v_mfma_f32_32x32x16_bf16 v[22:37], v[134:137], v[204:207], v[22:37]
	s_setprio 0
	s_andn2_b64 vcc, exec, s[66:67]
	s_cbranch_vccnz .LBB0_1105
	s_mul_hi_u32 s19, s1, 0xaaaaaaab
	s_lshr_b32 s19, s19, 2
	s_mul_i32 s19, s19, 0xffff0d00
	s_add_i32 s19, s19, 0
	s_add_i32 s19, s19, s81
	v_add_u32_e32 v1, s19, v242
	v_add_u32_e32 v200, s14, v1
	v_add3_u32 v134, v200, v231, v232
	v_add3_u32 v138, v200, v230, v232
	ds_read_b128 v[134:137], v134
	ds_read_b128 v[204:207], v138
	v_add3_u32 v208, v200, v228, v232
	ds_read_b128 v[248:251], v208
	s_setprio 1
	s_waitcnt lgkmcnt(2)
	v_mfma_f32_32x32x16_bf16 v[134:149], v[134:137], v[194:197], 0
	s_waitcnt lgkmcnt(1)
	v_mfma_f32_32x32x16_bf16 v[134:149], v[204:207], v[190:193], v[134:149]
	v_add3_u32 v208, v200, v227, v232
	ds_read_b128 v[204:207], v208
	s_waitcnt lgkmcnt(1)
	v_mfma_f32_32x32x16_bf16 v[134:149], v[248:251], v[186:189], v[134:149]
	v_add3_u32 v208, v200, v236, v232
	ds_read_b128 v[248:251], v208
	s_waitcnt lgkmcnt(1)
	v_mfma_f32_32x32x16_bf16 v[134:149], v[204:207], v[182:185], v[134:149]
	v_add3_u32 v208, v200, v235, v232
	ds_read_b128 v[204:207], v208
	s_waitcnt lgkmcnt(1)
	v_mfma_f32_32x32x16_bf16 v[134:149], v[248:251], v[178:181], v[134:149]
	v_add3_u32 v208, v200, v234, v232
	ds_read_b128 v[248:251], v208
	s_waitcnt lgkmcnt(1)
	v_mfma_f32_32x32x16_bf16 v[134:149], v[204:207], v[174:177], v[134:149]
	v_add3_u32 v208, v200, v233, v232
	ds_read_b128 v[204:207], v208
	s_waitcnt lgkmcnt(1)
	v_mfma_f32_32x32x16_bf16 v[134:149], v[248:251], v[170:173], v[134:149]
	v_add3_u32 v208, v1, v231, v226
	ds_read_b128 v[248:251], v208 offset:8192
	s_waitcnt lgkmcnt(1)
	v_mfma_f32_32x32x16_bf16 v[134:149], v[204:207], v[166:169], v[134:149]
	v_add3_u32 v208, v1, v230, v226
	ds_read_b128 v[204:207], v208 offset:8192
	s_waitcnt lgkmcnt(1)
	v_mfma_f32_32x32x16_bf16 v[134:149], v[248:251], v[162:165], v[134:149]
	v_add3_u32 v208, v1, v228, v226
	ds_read_b128 v[248:251], v208 offset:8192
	s_waitcnt lgkmcnt(1)
	v_mfma_f32_32x32x16_bf16 v[134:149], v[204:207], v[158:161], v[134:149]
	v_add3_u32 v208, v1, v227, v226
	ds_read_b128 v[204:207], v208 offset:8192
	s_waitcnt lgkmcnt(1)
	v_mfma_f32_32x32x16_bf16 v[134:149], v[248:251], v[154:157], v[134:149]
	s_waitcnt lgkmcnt(0)
	v_mfma_f32_32x32x16_bf16 v[134:149], v[204:207], v[150:153], v[134:149]
	s_setprio 0
	v_add_u32_e32 v1, s15, v198
	v_add_u32_e32 v208, s19, v1
	v_add_u32_e32 v1, 0x1b900, v208
	ds_read_b128 v[204:207], v1
	v_add_u32_e32 v1, 0x1b920, v208
	ds_read_b128 v[248:251], v1
	s_waitcnt lgkmcnt(1)
	s_nop 5
	v_fma_f32 v1, v134, v204, -v213
	v_fma_f32 v134, v135, v205, -v213
	v_exp_f32_e32 v1, v1
	v_fma_f32 v135, v136, v206, -v213
	v_exp_f32_e32 v200, v134
	v_fma_f32 v136, v137, v207, -v213
	v_exp_f32_e32 v204, v135
	v_exp_f32_e32 v205, v136
	s_waitcnt lgkmcnt(0)
	v_fma_f32 v135, v138, v248, -v213
	v_add_f32_e32 v134, 0, v1
	v_exp_f32_e32 v206, v135
	v_add_f32_e32 v134, v200, v134
	v_add_f32_e32 v134, v204, v134
	v_add_f32_e32 v134, v205, v134
	v_add_f32_e32 v138, v206, v134
	v_fma_f32 v134, v139, v249, -v213
	v_exp_f32_e32 v207, v134
	v_fma_f32 v134, v140, v250, -v213
	v_exp_f32_e32 v248, v134
	v_fma_f32 v134, v141, v251, -v213
	v_exp_f32_e32 v249, v134
	v_add_u32_e32 v139, 0x1e180, v208
	v_add_f32_e32 v138, v207, v138
	ds_read_b128 v[134:137], v139
	v_add_f32_e32 v138, v248, v138
	v_add_f32_e32 v208, v249, v138
	ds_read_b128 v[138:141], v139 offset:32
	s_waitcnt lgkmcnt(1)
	v_fma_f32 v134, v142, v134, -v213
	v_exp_f32_e32 v134, v134
	v_fma_f32 v135, v143, v135, -v213
	s_waitcnt lgkmcnt(0)
	v_fma_f32 v138, v146, v138, -v213
	v_exp_f32_e32 v135, v135
	v_fma_f32 v136, v144, v136, -v213
	v_exp_f32_e32 v143, v138
	v_fma_f32 v138, v147, v139, -v213
	v_exp_f32_e32 v136, v136
	v_fma_f32 v137, v145, v137, -v213
	v_exp_f32_e32 v144, v138
	v_fma_f32 v138, v148, v140, -v213
	v_exp_f32_e32 v137, v137
	v_exp_f32_e32 v145, v138
	v_fma_f32 v138, v149, v141, -v213
	v_add_f32_e32 v142, v134, v208
	v_exp_f32_e32 v146, v138
	v_add_f32_e32 v142, v135, v142
	v_add_f32_e32 v142, v136, v142
	v_add_f32_e32 v142, v137, v142
	v_cvt_pk_bf16_f32 v138, v1, v200
	v_cvt_pk_bf16_f32 v139, v204, v205
	v_cvt_pk_bf16_f32 v140, v206, v207
	v_cvt_pk_bf16_f32 v141, v248, v249
	s_nop 0
	v_permlane32_swap_b32_e32 v138, v140
	v_permlane32_swap_b32_e32 v139, v141
	v_cvt_pk_bf16_f32 v134, v134, v135
	v_cvt_pk_bf16_f32 v135, v136, v137
	v_cvt_pk_bf16_f32 v136, v143, v144
	v_cvt_pk_bf16_f32 v137, v145, v146
	v_add_f32_e32 v1, v143, v142
	v_permlane32_swap_b32_e32 v134, v136
	v_permlane32_swap_b32_e32 v135, v137
	v_add_f32_e32 v1, v144, v1
	ds_write_b128 v223, v[138:141]
	ds_write_b128 v223, v[134:137] offset:16
	v_add_f32_e32 v1, v145, v1
	s_waitcnt lgkmcnt(0)
	v_add_f32_e32 v1, v146, v1
	v_add_f32_e32 v2, v2, v1
	s_branch .LBB0_1105
